# O3a q-up tile epilogue: the 16 rope-table loads issued 8 at a time (two halves) instead of pairwise with a wait after each
# baseline (speedup 1.0000x reference)
; template <int MT, class Epi>
; DI void gemm_tile(const u16* __restrict__ X, long ldx, const u16* __restrict__ W, long ldw, int K, char* smem,
;                   int m0, int n0, const Epi& epi, bool pre = false, const u16* Xn = nullptr, const u16* Wn = nullptr) {
;     ...
; #pragma unroll
;     for (int ks = 0; ks < 2; ++ks) {
;       bf16x8 xf[MT], wf[4];
;       const int ch = ((ks * 4 + g) ^ rsw) << 4;
; #pragma unroll
;       for (int i = 0; i < MT; ++i) xf[i] = *(const bf16x8*)(cur + (wm * 16 * MT + i * 16 + lr) * 128 + ch);
; #pragma unroll
;       for (int i = 0; i < 4; ++i) wf[i] = *(const bf16x8*)(cur + 16384 + (wn * 64 + i * 16 + lr) * 128 + ch);
; #pragma unroll
;       for (int nt = 0; nt < 4; ++nt)
; #pragma unroll
;         for (int mt = 0; mt < MT; ++mt)
;           acc[nt][mt] = __builtin_amdgcn_mfma_f32_16x16x32_bf16(wf[nt], xf[mt], acc[nt][mt], 0, 0, 0);
;   template <int NT, int MT> DI void run(f32x4 (&acc)[NT][MT], int mb, int nb) const {
;     ...
;     for (int q4 = 0; q4 < NT / 4; ++q4) {
;       const int grp = ((nb - g4) >> 6) + q4;
;       if ((grp % 3) == 2) {
; #pragma unroll
;         for (int mt = 0; mt < MT; ++mt) {
;           const int pos = tok_pos(mb + mt * 16);
; #pragma unroll
;           for (int nt = 0; nt < 2; ++nt)
; #pragma unroll
;             for (int j = 0; j < 4; ++j) {
;               const float2 cs = rope[pos * 32 + nt * 16 + g4 + j];
;               const float x1 = acc[q4 * 4 + nt][mt][j], x2 = acc[q4 * 4 + nt + 2][mt][j];
;               acc[q4 * 4 + nt][mt][j] = x1 * cs.x - x2 * cs.y;
;               acc[q4 * 4 + nt + 2][mt][j] = x2 * cs.x + x1 * cs.y;
.LBB0_110:
	v_add_u32_e32 v74, v74, v73
	ds_read_b128 v[66:69], v74 offset:49152
	v_add_u32_e32 v75, v75, v73
	ds_read_b128 v[78:81], v75 offset:32768
	ds_read_b128 v[82:85], v75 offset:34816
	ds_read_b128 v[86:89], v75 offset:36864
	ds_read_b128 v[90:93], v75 offset:38912
	s_lshl_b32 s5, s5, 7
	s_lshl_b32 s6, s6, 7
	v_lshlrev_b32_e32 v1, 6, v1
	s_waitcnt lgkmcnt(3)
	v_mfma_f32_16x16x32_bf16 v[6:9], v[66:69], v[78:81], v[6:9]
	s_waitcnt lgkmcnt(2)
	v_mfma_f32_16x16x32_bf16 v[10:13], v[66:69], v[82:85], v[10:13]
	s_waitcnt lgkmcnt(1)
	v_mfma_f32_16x16x32_bf16 v[14:17], v[66:69], v[86:89], v[14:17]
	s_waitcnt lgkmcnt(0)
	v_mfma_f32_16x16x32_bf16 v[18:21], v[66:69], v[90:93], v[18:21]
	ds_read_b128 v[66:69], v74 offset:51200
	s_waitcnt lgkmcnt(0)
	v_mfma_f32_16x16x32_bf16 v[22:25], v[66:69], v[78:81], v[22:25]
	v_mfma_f32_16x16x32_bf16 v[26:29], v[66:69], v[82:85], v[26:29]
	v_mfma_f32_16x16x32_bf16 v[30:33], v[66:69], v[86:89], v[30:33]
	v_mfma_f32_16x16x32_bf16 v[34:37], v[66:69], v[90:93], v[34:37]
	ds_read_b128 v[66:69], v74 offset:53248
	s_waitcnt lgkmcnt(0)
	v_mfma_f32_16x16x32_bf16 v[94:97], v[66:69], v[78:81], v[38:41]
	s_nop 2
	ds_read_b128 v[38:41], v74 offset:55296
	v_add_u32_e32 v74, v76, v73
	v_or3_b32 v76, v1, s6, v71
	v_mfma_f32_16x16x32_bf16 v[98:101], v[66:69], v[82:85], v[42:45]
	v_or_b32_e32 v75, 16, v76
	s_nop 1
	ds_read_b128 v[42:45], v74 offset:49152
	v_mfma_f32_16x16x32_bf16 v[102:105], v[66:69], v[86:89], v[46:49]
	s_waitcnt lgkmcnt(1)
	v_mfma_f32_16x16x32_bf16 v[78:81], v[38:41], v[78:81], v[54:57]
	v_mfma_f32_16x16x32_bf16 v[82:85], v[38:41], v[82:85], v[58:61]
	v_mfma_f32_16x16x32_bf16 v[86:89], v[38:41], v[86:89], v[62:65]
	v_mfma_f32_16x16x32_bf16 v[2:5], v[38:41], v[90:93], v[2:5]
	v_add_u32_e32 v38, v77, v73
	ds_read_b128 v[106:109], v38 offset:36864
	ds_read_b128 v[110:113], v38 offset:38912
	v_mfma_f32_16x16x32_bf16 v[66:69], v[66:69], v[90:93], v[50:53]
	ds_read_b128 v[90:93], v38 offset:32768
	v_lshl_add_u32 v77, v72, 6, s5
	v_ashrrev_i32_e32 v1, 6, v77
	s_waitcnt lgkmcnt(0)
	v_mfma_f32_16x16x32_bf16 v[62:65], v[42:45], v[90:93], v[6:9]
	s_mov_b32 s5, 0x55555556
	s_nop 1
	ds_read_b128 v[6:9], v38 offset:34816
	s_waitcnt lgkmcnt(0)
	v_mfma_f32_16x16x32_bf16 v[58:61], v[42:45], v[6:9], v[10:13]
	s_nop 2
	ds_read_b128 v[10:13], v74 offset:51200
	v_mfma_f32_16x16x32_bf16 v[54:57], v[42:45], v[106:109], v[14:17]
	v_mfma_f32_16x16x32_bf16 v[46:49], v[42:45], v[110:113], v[18:21]
	s_waitcnt lgkmcnt(0)
	v_mfma_f32_16x16x32_bf16 v[50:53], v[10:13], v[90:93], v[22:25]
	v_mfma_f32_16x16x32_bf16 v[42:45], v[10:13], v[6:9], v[26:29]
	v_mfma_f32_16x16x32_bf16 v[38:41], v[10:13], v[106:109], v[30:33]
	v_mfma_f32_16x16x32_bf16 v[34:37], v[10:13], v[110:113], v[34:37]
	ds_read_b128 v[10:13], v74 offset:53248
	s_waitcnt lgkmcnt(0)
	v_mfma_f32_16x16x32_bf16 v[30:33], v[10:13], v[90:93], v[94:97]
	s_nop 2
	ds_read_b128 v[94:97], v74 offset:55296
	v_or_b32_e32 v74, 32, v76
	v_mfma_f32_16x16x32_bf16 v[22:25], v[10:13], v[110:113], v[66:69]
	s_nop 2
	v_mul_hi_i32 v66, v1, s5
	v_lshrrev_b32_e32 v67, 31, v66
	v_mfma_f32_16x16x32_bf16 v[26:29], v[10:13], v[6:9], v[98:101]
	v_mfma_f32_16x16x32_bf16 v[18:21], v[10:13], v[106:109], v[102:105]
	s_waitcnt lgkmcnt(0)
	v_mfma_f32_16x16x32_bf16 v[10:13], v[94:97], v[6:9], v[82:85]
	v_add_u32_e32 v6, v66, v67
	v_lshl_add_u32 v6, v6, 1, v6
	v_sub_u32_e32 v1, v1, v6
	v_mfma_f32_16x16x32_bf16 v[14:17], v[94:97], v[90:93], v[78:81]
	v_cmp_ne_u32_e32 vcc, 2, v1
	v_or_b32_e32 v1, 48, v76
	v_mfma_f32_16x16x32_bf16 v[6:9], v[94:97], v[106:109], v[86:89]
	v_mfma_f32_16x16x32_bf16 v[2:5], v[94:97], v[110:113], v[2:5]
	s_and_saveexec_b64 s[6:7], vcc
	s_xor_b64 s[40:41], exec, s[6:7]
	v_or_b32_e32 v75, 16, v76
	v_or_b32_e32 v74, 32, v76
	v_or_b32_e32 v1, 48, v76
	s_or_saveexec_b64 s[40:41], s[40:41]
	v_lshlrev_b32_e32 v78, 2, v70
	s_xor_b64 exec, exec, s[40:41]
	s_cbranch_execz .LBB0_97
	s_movk_i32 s5, 0x4000
	v_cmp_gt_i32_e32 vcc, s5, v76
	v_and_b32_e32 v128, 0x1fcf, v76
	v_or_b32_e32 v129, 0x400, v71
	v_cndmask_b32_e32 v186, v129, v128, vcc
	v_lshlrev_b32_e32 v187, 3, v78
	v_lshl_or_b32 v188, v186, 8, v187
	global_load_dwordx4 v[92:95], v188, s[82:83] offset:16
	global_load_dwordx4 v[96:99], v188, s[82:83]
	s_movk_i32 s5, 0x3ff0
	v_cmp_gt_i32_e32 vcc, s5, v76
	s_movk_i32 s5, 0x1fdf
	global_load_dwordx4 v[100:103], v188, s[82:83] offset:144
	global_load_dwordx4 v[104:107], v188, s[82:83] offset:128
	v_bitop3_b32 v189, v76, s5, 16 bitop3:0xc8
	v_and_or_b32 v108, v75, 31, v213
	v_cndmask_b32_e32 v109, v108, v189, vcc
	v_lshl_or_b32 v110, v109, 8, v187
	global_load_dwordx4 v[112:115], v110, s[82:83] offset:16
	global_load_dwordx4 v[116:119], v110, s[82:83]
	global_load_dwordx4 v[120:123], v110, s[82:83] offset:144
	global_load_dwordx4 v[124:127], v110, s[82:83] offset:128
	s_nop 0
	s_nop 0
	s_nop 0
	s_nop 0
	s_nop 0
	s_nop 0
	s_nop 0
	s_nop 0
	s_nop 0
	s_nop 0
	s_nop 0
	s_nop 0
	s_waitcnt vmcnt(7)
	v_mul_f32_e32 v84, v64, v92
	s_waitcnt vmcnt(6)
	v_mov_b32_e32 v73, v98
	v_mov_b32_e32 v82, v97
	v_mov_b32_e32 v72, v96
	v_mov_b32_e32 v148, v82
	v_mov_b32_e32 v149, v99
	v_pk_mul_f32 v[80:81], v[62:63], v[148:149]
	v_mov_b32_e32 v150, v82
	v_mov_b32_e32 v151, v99
	v_pk_mul_f32 v[82:83], v[30:31], v[150:151]
	v_mul_f32_e32 v86, v32, v93
	v_mul_f32_e32 v88, v32, v92
	v_mul_f32_e32 v90, v64, v93
	v_mov_b32_e32 v32, v65
	v_mov_b32_e32 v64, v33
	v_pk_mul_f32 v[68:69], v[32:33], v[94:95]
	v_pk_fma_f32 v[62:63], v[62:63], v[72:73], v[82:83] neg_lo:[0,0,1] neg_hi:[0,0,1]
	v_pk_mul_f32 v[32:33], v[64:65], v[94:95]
	v_pk_fma_f32 v[30:31], v[30:31], v[72:73], v[80:81]
	s_nop 0
	s_nop 0
	v_mov_b32_e32 v85, v68
	v_mov_b32_e32 v87, v69
	v_mov_b32_e32 v89, v32
	v_mov_b32_e32 v91, v33
	v_pk_add_f32 v[68:69], v[84:85], v[86:87] neg_lo:[0,1] neg_hi:[0,1]
	v_pk_add_f32 v[32:33], v[88:89], v[90:91]
	s_waitcnt vmcnt(5)
;   template <int NT, int MT> DI void run(f32x4 (&acc)[NT][MT], int mb, int nb) const {
;     ...
; #pragma unroll
;         for (int mt = 0; mt < MT; ++mt) {
;           const int pos = tok_pos(mb + mt * 16);
; #pragma unroll
;           for (int nt = 0; nt < 2; ++nt)
; #pragma unroll
;             for (int j = 0; j < 4; ++j) {
;               const float2 cs = rope[pos * 32 + nt * 16 + g4 + j];
;               const float x1 = acc[q4 * 4 + nt][mt][j], x2 = acc[q4 * 4 + nt + 2][mt][j];
;               acc[q4 * 4 + nt][mt][j] = x1 * cs.x - x2 * cs.y;
;               acc[q4 * 4 + nt + 2][mt][j] = x2 * cs.x + x1 * cs.y;
	v_mul_f32_e32 v84, v52, v100
	v_mul_f32_e32 v86, v16, v101
	v_mul_f32_e32 v88, v16, v100
	v_mul_f32_e32 v90, v52, v101
	v_mov_b32_e32 v16, v53
	v_mov_b32_e32 v52, v17
	v_pk_mul_f32 v[70:71], v[16:17], v[102:103]
	v_pk_mul_f32 v[16:17], v[52:53], v[102:103]
	s_nop 0
	s_nop 0
	s_waitcnt vmcnt(4)
	v_mov_b32_e32 v65, v106
	v_mov_b32_e32 v82, v105
	s_nop 0
	v_mov_b32_e32 v64, v104
	v_mov_b32_e32 v152, v82
	v_mov_b32_e32 v153, v107
	v_pk_mul_f32 v[80:81], v[50:51], v[152:153]
	v_mov_b32_e32 v154, v82
	v_mov_b32_e32 v155, v107
	v_pk_mul_f32 v[82:83], v[14:15], v[154:155]
	v_mov_b32_e32 v85, v70
	v_mov_b32_e32 v87, v71
	s_nop 0
	v_pk_fma_f32 v[50:51], v[50:51], v[64:65], v[82:83] neg_lo:[0,0,1] neg_hi:[0,0,1]
	v_pk_add_f32 v[70:71], v[84:85], v[86:87] neg_lo:[0,1] neg_hi:[0,1]
	v_pk_fma_f32 v[14:15], v[14:15], v[64:65], v[80:81]
	s_nop 0
	s_nop 0
	v_mov_b32_e32 v89, v16
	v_mov_b32_e32 v91, v17
	v_pk_add_f32 v[16:17], v[88:89], v[90:91]
	s_movk_i32 s5, 0x3fe0
	v_cmp_gt_i32_e32 vcc, s5, v76
	s_movk_i32 s5, 0x1fef
	s_waitcnt vmcnt(3)
	v_mul_f32_e32 v88, v60, v113
	s_waitcnt vmcnt(2)
	v_mov_b32_e32 v53, v118
	v_mov_b32_e32 v86, v117
	v_mov_b32_e32 v52, v116
	v_mov_b32_e32 v156, v86
	v_mov_b32_e32 v157, v119
	v_pk_mul_f32 v[64:65], v[58:59], v[156:157]
	v_mov_b32_e32 v158, v86
	v_mov_b32_e32 v159, v119
	v_pk_mul_f32 v[72:73], v[26:27], v[158:159]
	v_mul_f32_e32 v84, v60, v112
	v_mul_f32_e32 v86, v28, v113
	v_mul_f32_e32 v80, v28, v112
	v_mov_b32_e32 v28, v61
	v_mov_b32_e32 v60, v29
	v_pk_mul_f32 v[90:91], v[28:29], v[114:115]
	v_pk_mul_f32 v[28:29], v[60:61], v[114:115]
	v_mov_b32_e32 v85, v90
	v_mov_b32_e32 v87, v91
	v_mov_b32_e32 v81, v28
	v_mov_b32_e32 v89, v29
	v_pk_fma_f32 v[58:59], v[58:59], v[52:53], v[72:73] neg_lo:[0,0,1] neg_hi:[0,0,1]
	v_pk_add_f32 v[72:73], v[84:85], v[86:87] neg_lo:[0,1] neg_hi:[0,1]
	v_pk_add_f32 v[28:29], v[80:81], v[88:89]
	s_nop 0
	s_nop 0
	v_pk_fma_f32 v[26:27], v[26:27], v[52:53], v[64:65]
	s_waitcnt vmcnt(1)
	v_mul_f32_e32 v88, v44, v121
	s_waitcnt vmcnt(0)
	v_mov_b32_e32 v66, v187
	v_mov_b32_e32 v67, v129
	v_mov_b32_e32 v79, v110
	v_mov_b32_e32 v80, v120
	v_mov_b32_e32 v81, v121
	v_mov_b32_e32 v82, v122
	v_mov_b32_e32 v83, v123
	v_mov_b32_e32 v84, v124
	v_mov_b32_e32 v85, v125
	v_mov_b32_e32 v86, v126
	v_mov_b32_e32 v87, v127
	v_bitop3_b32 v128, v76, s5, 32 bitop3:0xc8
	v_cndmask_b32_e32 v129, v67, v128, vcc
	v_lshl_or_b32 v186, v129, 8, v66
	global_load_dwordx4 v[92:95], v186, s[82:83] offset:16
	global_load_dwordx4 v[96:99], v186, s[82:83]
	s_movk_i32 s5, 0x3fd0
	v_cmp_gt_i32_e32 vcc, s5, v76
	s_movk_i32 s5, 0x1fff
	global_load_dwordx4 v[100:103], v186, s[82:83] offset:144
	global_load_dwordx4 v[104:107], v186, s[82:83] offset:128
	v_bitop3_b32 v187, v76, s5, 48 bitop3:0xc8
	v_and_or_b32 v188, v1, 31, v213
	v_cndmask_b32_e32 v189, v188, v187, vcc
	v_lshl_or_b32 v108, v189, 8, v66
	global_load_dwordx4 v[110:113], v108, s[82:83] offset:16
	global_load_dwordx4 v[114:117], v108, s[82:83]
	global_load_dwordx4 v[118:121], v108, s[82:83] offset:144
	global_load_dwordx4 v[122:125], v108, s[82:83] offset:128
	v_mov_b32_e32 v61, v86
	v_mov_b32_e32 v86, v85
	v_mov_b32_e32 v60, v84
	v_pk_mul_f32 v[64:65], v[42:43], v[86:87]
	v_pk_mul_f32 v[52:53], v[10:11], v[86:87]
	v_mul_f32_e32 v84, v44, v80
	v_mul_f32_e32 v86, v12, v81
	v_mul_f32_e32 v80, v12, v80
	v_mov_b32_e32 v12, v45
	v_mov_b32_e32 v44, v13
	v_pk_mul_f32 v[90:91], v[12:13], v[82:83]
	v_pk_mul_f32 v[12:13], v[44:45], v[82:83]
	s_nop 0
	s_nop 0
	v_mov_b32_e32 v85, v90
	v_mov_b32_e32 v87, v91
	v_mov_b32_e32 v81, v12
	v_mov_b32_e32 v89, v13
	s_nop 0
	v_pk_fma_f32 v[42:43], v[42:43], v[60:61], v[52:53] neg_lo:[0,0,1] neg_hi:[0,0,1]
	v_pk_add_f32 v[52:53], v[84:85], v[86:87] neg_lo:[0,1] neg_hi:[0,1]
	v_pk_add_f32 v[12:13], v[80:81], v[88:89]
	s_nop 0
	s_nop 0
	v_pk_fma_f32 v[10:11], v[10:11], v[60:61], v[64:65]
	s_nop 0
	s_nop 0
	s_nop 0
	s_waitcnt vmcnt(7)
	v_mul_f32_e32 v88, v56, v93
	s_waitcnt vmcnt(6)
;   template <int NT, int MT> DI void run(f32x4 (&acc)[NT][MT], int mb, int nb) const {
;     ...
; #pragma unroll
;         for (int mt = 0; mt < MT; ++mt) {
;           const int pos = tok_pos(mb + mt * 16);
; #pragma unroll
;           for (int nt = 0; nt < 2; ++nt)
; #pragma unroll
;             for (int j = 0; j < 4; ++j) {
;               const float2 cs = rope[pos * 32 + nt * 16 + g4 + j];
;               const float x1 = acc[q4 * 4 + nt][mt][j], x2 = acc[q4 * 4 + nt + 2][mt][j];
;               acc[q4 * 4 + nt][mt][j] = x1 * cs.x - x2 * cs.y;
;               acc[q4 * 4 + nt + 2][mt][j] = x2 * cs.x + x1 * cs.y;
	v_mov_b32_e32 v45, v98
	v_mov_b32_e32 v86, v97
	v_mov_b32_e32 v44, v96
	v_mov_b32_e32 v126, v86
	v_mov_b32_e32 v127, v99
	v_pk_mul_f32 v[64:65], v[54:55], v[126:127]
	v_mov_b32_e32 v148, v86
	v_mov_b32_e32 v149, v99
	v_pk_mul_f32 v[60:61], v[18:19], v[148:149]
	v_mul_f32_e32 v84, v56, v92
	v_mul_f32_e32 v86, v20, v93
	v_mul_f32_e32 v80, v20, v92
	v_mov_b32_e32 v20, v57
	v_mov_b32_e32 v56, v21
	v_pk_mul_f32 v[90:91], v[20:21], v[94:95]
	v_pk_mul_f32 v[20:21], v[56:57], v[94:95]
	v_mov_b32_e32 v85, v90
	v_mov_b32_e32 v87, v91
	v_mov_b32_e32 v81, v20
	v_mov_b32_e32 v89, v21
	v_pk_fma_f32 v[54:55], v[54:55], v[44:45], v[60:61] neg_lo:[0,0,1] neg_hi:[0,0,1]
	v_pk_add_f32 v[60:61], v[84:85], v[86:87] neg_lo:[0,1] neg_hi:[0,1]
	v_pk_add_f32 v[20:21], v[80:81], v[88:89]
	s_nop 0
	s_nop 0
	v_pk_fma_f32 v[18:19], v[18:19], v[44:45], v[64:65]
	s_waitcnt vmcnt(5)
	v_mul_f32_e32 v88, v40, v101
	s_waitcnt vmcnt(4)
	v_mov_b32_e32 v57, v106
	v_mov_b32_e32 v86, v105
	v_mov_b32_e32 v56, v104
	v_mov_b32_e32 v150, v86
	v_mov_b32_e32 v151, v107
	v_pk_mul_f32 v[64:65], v[38:39], v[150:151]
	v_mov_b32_e32 v152, v86
	v_mov_b32_e32 v153, v107
	v_pk_mul_f32 v[44:45], v[6:7], v[152:153]
	v_mul_f32_e32 v84, v40, v100
	v_mul_f32_e32 v86, v8, v101
	v_mul_f32_e32 v80, v8, v100
	v_mov_b32_e32 v8, v41
	v_mov_b32_e32 v40, v9
	v_pk_mul_f32 v[90:91], v[8:9], v[102:103]
	v_pk_mul_f32 v[8:9], v[40:41], v[102:103]
	s_nop 0
	s_nop 0
	s_nop 0
	v_mov_b32_e32 v81, v8
	v_mov_b32_e32 v89, v9
	s_nop 0
	v_pk_fma_f32 v[6:7], v[6:7], v[56:57], v[64:65]
	v_pk_add_f32 v[8:9], v[80:81], v[88:89]
	s_nop 0
	s_nop 0
	v_mov_b32_e32 v85, v90
	v_mov_b32_e32 v87, v91
	v_pk_fma_f32 v[38:39], v[38:39], v[56:57], v[44:45] neg_lo:[0,0,1] neg_hi:[0,0,1]
	v_pk_add_f32 v[44:45], v[84:85], v[86:87] neg_lo:[0,1] neg_hi:[0,1]
	s_waitcnt vmcnt(3)
	v_mul_f32_e32 v84, v24, v111
	s_waitcnt vmcnt(2)
	v_mov_b32_e32 v41, v116
	v_mov_b32_e32 v82, v115
	v_mov_b32_e32 v40, v114
	v_mov_b32_e32 v154, v82
	v_mov_b32_e32 v155, v117
	v_pk_mul_f32 v[80:81], v[46:47], v[154:155]
	v_mov_b32_e32 v156, v82
	v_mov_b32_e32 v157, v117
	v_pk_mul_f32 v[56:57], v[22:23], v[156:157]
	v_mul_f32_e32 v82, v48, v110
	v_mul_f32_e32 v64, v24, v110
	v_mul_f32_e32 v86, v48, v111
	v_mov_b32_e32 v24, v49
	v_mov_b32_e32 v48, v25
	v_pk_mul_f32 v[88:89], v[24:25], v[112:113]
	v_pk_mul_f32 v[24:25], v[48:49], v[112:113]
	v_mov_b32_e32 v83, v88
	v_mov_b32_e32 v85, v89
	v_mov_b32_e32 v65, v24
	v_mov_b32_e32 v87, v25
	v_pk_fma_f32 v[46:47], v[46:47], v[40:41], v[56:57] neg_lo:[0,0,1] neg_hi:[0,0,1]
	v_pk_add_f32 v[56:57], v[82:83], v[84:85] neg_lo:[0,1] neg_hi:[0,1]
	v_pk_fma_f32 v[22:23], v[22:23], v[40:41], v[80:81]
	v_pk_add_f32 v[24:25], v[64:65], v[86:87]
	s_nop 0
	s_nop 0
	s_waitcnt vmcnt(1)
	v_mul_f32_e32 v84, v4, v119
	s_waitcnt vmcnt(0)
	v_mov_b32_e32 v41, v124
	v_mov_b32_e32 v82, v123
	v_mov_b32_e32 v40, v122
	v_mov_b32_e32 v158, v82
	v_mov_b32_e32 v159, v125
	v_pk_mul_f32 v[48:49], v[34:35], v[158:159]
	v_mov_b32_e32 v160, v82
	v_mov_b32_e32 v161, v125
	v_pk_mul_f32 v[80:81], v[2:3], v[160:161]
	v_mul_f32_e32 v82, v36, v118
	v_mul_f32_e32 v64, v4, v118
	v_mov_b32_e32 v4, v37
	v_mul_f32_e32 v86, v36, v119
	v_pk_mul_f32 v[88:89], v[4:5], v[120:121]
	v_mov_b32_e32 v36, v5
	v_mov_b32_e32 v83, v88
	v_mov_b32_e32 v85, v89
	v_pk_mul_f32 v[4:5], v[36:37], v[120:121]
	v_pk_fma_f32 v[34:35], v[34:35], v[40:41], v[80:81] neg_lo:[0,0,1] neg_hi:[0,0,1]
	v_pk_add_f32 v[80:81], v[82:83], v[84:85] neg_lo:[0,1] neg_hi:[0,1]
	v_mov_b32_e32 v65, v4
	v_mov_b32_e32 v87, v5
	v_pk_fma_f32 v[2:3], v[2:3], v[40:41], v[48:49]
	v_pk_add_f32 v[4:5], v[64:65], v[86:87]
	v_mov_b32_e32 v36, v80
	v_mov_b32_e32 v37, v81
	v_mov_b32_e32 v40, v44
	v_mov_b32_e32 v41, v45
	v_mov_b32_e32 v44, v52
	v_mov_b32_e32 v45, v53
	v_mov_b32_e32 v52, v70
	v_mov_b32_e32 v53, v71
	v_mov_b32_e32 v48, v56
	v_mov_b32_e32 v49, v57
	v_mov_b32_e32 v56, v60
	v_mov_b32_e32 v57, v61
	v_mov_b32_e32 v60, v72
	v_mov_b32_e32 v61, v73
	v_mov_b32_e32 v64, v68
	v_mov_b32_e32 v65, v69
	v_mov_b32_e32 v66, v120
	v_mov_b32_e32 v67, v121
	v_mov_b32_e32 v79, v108
	s_branch .LBB0_97

; template <int MT, class Epi>
; DI void gemm_tile(const u16* __restrict__ X, long ldx, const u16* __restrict__ W, long ldw, int K, char* smem,
;                   int m0, int n0, const Epi& epi, bool pre = false, const u16* Xn = nullptr, const u16* Wn = nullptr) {
;     ...
; #pragma unroll
;     for (int ks = 0; ks < 2; ++ks) {
;       bf16x8 xf[MT], wf[4];
;       const int ch = ((ks * 4 + g) ^ rsw) << 4;
; #pragma unroll
;       for (int i = 0; i < MT; ++i) xf[i] = *(const bf16x8*)(cur + (wm * 16 * MT + i * 16 + lr) * 128 + ch);
; #pragma unroll
;       for (int i = 0; i < 4; ++i) wf[i] = *(const bf16x8*)(cur + 16384 + (wn * 64 + i * 16 + lr) * 128 + ch);
; #pragma unroll
;       for (int nt = 0; nt < 4; ++nt)
; #pragma unroll
;         for (int mt = 0; mt < MT; ++mt)
;           acc[nt][mt] = __builtin_amdgcn_mfma_f32_16x16x32_bf16(wf[nt], xf[mt], acc[nt][mt], 0, 0, 0);
;   template <int NT, int MT> DI void run(f32x4 (&acc)[NT][MT], int mb, int nb) const {
;     ...
;     for (int q4 = 0; q4 < NT / 4; ++q4) {
;       const int grp = ((nb - g4) >> 6) + q4;
;       if ((grp % 3) == 2) {
; #pragma unroll
;         for (int mt = 0; mt < MT; ++mt) {
;           const int pos = tok_pos(mb + mt * 16);
; #pragma unroll
;           for (int nt = 0; nt < 2; ++nt)
; #pragma unroll
;             for (int j = 0; j < 4; ++j) {
;               const float2 cs = rope[pos * 32 + nt * 16 + g4 + j];
;               const float x1 = acc[q4 * 4 + nt][mt][j], x2 = acc[q4 * 4 + nt + 2][mt][j];
;               acc[q4 * 4 + nt][mt][j] = x1 * cs.x - x2 * cs.y;
;               acc[q4 * 4 + nt + 2][mt][j] = x2 * cs.x + x1 * cs.y;
.LBB0_992:
	v_add_u32_e32 v73, v73, v72
	ds_read_b128 v[64:67], v73 offset:49152
	v_add_u32_e32 v74, v74, v72
	ds_read_b128 v[78:81], v74 offset:32768
	ds_read_b128 v[82:85], v74 offset:34816
	ds_read_b128 v[86:89], v74 offset:36864
	ds_read_b128 v[90:93], v74 offset:38912
	s_lshl_b32 s5, s5, 7
	s_lshl_b32 s6, s6, 7
	s_waitcnt lgkmcnt(3)
	v_mfma_f32_16x16x32_bf16 v[4:7], v[64:67], v[78:81], v[4:7]
	s_waitcnt lgkmcnt(2)
	v_mfma_f32_16x16x32_bf16 v[8:11], v[64:67], v[82:85], v[8:11]
	s_waitcnt lgkmcnt(1)
	v_mfma_f32_16x16x32_bf16 v[12:15], v[64:67], v[86:89], v[12:15]
	s_waitcnt lgkmcnt(0)
	v_mfma_f32_16x16x32_bf16 v[16:19], v[64:67], v[90:93], v[16:19]
	ds_read_b128 v[64:67], v73 offset:51200
	s_waitcnt lgkmcnt(0)
	v_mfma_f32_16x16x32_bf16 v[20:23], v[64:67], v[78:81], v[20:23]
	v_mfma_f32_16x16x32_bf16 v[24:27], v[64:67], v[82:85], v[24:27]
	v_mfma_f32_16x16x32_bf16 v[28:31], v[64:67], v[86:89], v[28:31]
	v_mfma_f32_16x16x32_bf16 v[64:67], v[64:67], v[90:93], v[32:35]
	s_nop 2
	ds_read_b128 v[32:35], v73 offset:53248
	s_waitcnt lgkmcnt(0)
	v_mfma_f32_16x16x32_bf16 v[36:39], v[32:35], v[78:81], v[36:39]
	v_mfma_f32_16x16x32_bf16 v[94:97], v[32:35], v[82:85], v[40:43]
	v_mfma_f32_16x16x32_bf16 v[98:101], v[32:35], v[86:89], v[44:47]
	v_mfma_f32_16x16x32_bf16 v[102:105], v[32:35], v[90:93], v[48:51]
	ds_read_b128 v[32:35], v73 offset:55296
	v_add_u32_e32 v73, v75, v72
	ds_read_b128 v[40:43], v73 offset:49152
	s_waitcnt lgkmcnt(1)
	v_mfma_f32_16x16x32_bf16 v[78:81], v[32:35], v[78:81], v[52:55]
	v_mfma_f32_16x16x32_bf16 v[82:85], v[32:35], v[82:85], v[56:59]
	v_mfma_f32_16x16x32_bf16 v[86:89], v[32:35], v[86:89], v[60:63]
	v_mfma_f32_16x16x32_bf16 v[90:93], v[32:35], v[90:93], v[0:3]
	v_add_u32_e32 v32, v76, v72
	ds_read_b128 v[74:77], v32 offset:36864
	ds_read_b128 v[106:109], v32 offset:38912
	ds_read_b128 v[0:3], v32 offset:32768
	s_waitcnt lgkmcnt(0)
	v_mfma_f32_16x16x32_bf16 v[60:63], v[40:43], v[0:3], v[4:7]
	s_nop 2
	ds_read_b128 v[4:7], v32 offset:34816
	s_waitcnt lgkmcnt(0)
	v_mfma_f32_16x16x32_bf16 v[56:59], v[40:43], v[4:7], v[8:11]
	s_nop 2
	ds_read_b128 v[8:11], v73 offset:51200
	v_mfma_f32_16x16x32_bf16 v[52:55], v[40:43], v[74:77], v[12:15]
	v_mfma_f32_16x16x32_bf16 v[44:47], v[40:43], v[106:109], v[16:19]
	s_waitcnt lgkmcnt(0)
	v_mfma_f32_16x16x32_bf16 v[48:51], v[8:11], v[0:3], v[20:23]
	v_mfma_f32_16x16x32_bf16 v[40:43], v[8:11], v[4:7], v[24:27]
	v_mfma_f32_16x16x32_bf16 v[32:35], v[8:11], v[74:77], v[28:31]
	v_mfma_f32_16x16x32_bf16 v[28:31], v[8:11], v[106:109], v[64:67]
	ds_read_b128 v[8:11], v73 offset:53248
	s_waitcnt lgkmcnt(0)
	v_mfma_f32_16x16x32_bf16 v[24:27], v[8:11], v[0:3], v[36:39]
	s_nop 2
	ds_read_b128 v[36:39], v73 offset:55296
	v_lshl_add_u32 v73, v71, 6, s5
	v_ashrrev_i32_e32 v64, 6, v73
	s_mov_b32 s5, 0x55555556
	v_mul_hi_i32 v65, v64, s5
	s_waitcnt lgkmcnt(0)
	v_mfma_f32_16x16x32_bf16 v[12:15], v[36:39], v[0:3], v[78:81]
	v_lshlrev_b32_e32 v0, 6, v70
	v_lshrrev_b32_e32 v66, 31, v65
	v_or3_b32 v72, v0, s6, v69
	v_mfma_f32_16x16x32_bf16 v[20:23], v[8:11], v[4:7], v[94:97]
	v_add_u32_e32 v65, v65, v66
	v_lshl_add_u32 v65, v65, 1, v65
	v_sub_u32_e32 v64, v64, v65
	v_mfma_f32_16x16x32_bf16 v[16:19], v[8:11], v[74:77], v[98:101]
	v_cmp_ne_u32_e32 vcc, 2, v64
	v_mfma_f32_16x16x32_bf16 v[8:11], v[8:11], v[106:109], v[102:105]
	v_mfma_f32_16x16x32_bf16 v[4:7], v[36:39], v[4:7], v[82:85]
	v_mfma_f32_16x16x32_bf16 v[0:3], v[36:39], v[74:77], v[86:89]
	v_mfma_f32_16x16x32_bf16 v[36:39], v[36:39], v[106:109], v[90:93]
	s_and_saveexec_b64 s[6:7], vcc
	s_xor_b64 s[40:41], exec, s[6:7]
	v_or_b32_e32 v74, 16, v72
	v_or_b32_e32 v75, 32, v72
	v_or_b32_e32 v77, 48, v72
	s_or_saveexec_b64 s[40:41], s[40:41]
	v_lshlrev_b32_e32 v76, 2, v68
	s_xor_b64 exec, exec, s[40:41]
	s_cbranch_execz .LBB0_979
	s_movk_i32 s5, 0x4000
	v_cmp_gt_i32_e32 vcc, s5, v72
	v_and_b32_e32 v90, 0x1fcf, v72
	v_or_b32_e32 v91, 0x400, v69
	v_cndmask_b32_e32 v128, v91, v90, vcc
	v_lshlrev_b32_e32 v129, 3, v76
	v_lshl_or_b32 v186, v128, 8, v129
	global_load_dwordx4 v[92:95], v186, s[82:83] offset:16
	global_load_dwordx4 v[96:99], v186, s[82:83]
	s_movk_i32 s5, 0x3ff0
	v_cmp_gt_i32_e32 vcc, s5, v72
	s_movk_i32 s5, 0x1fdf
	global_load_dwordx4 v[100:103], v186, s[82:83] offset:144
	global_load_dwordx4 v[104:107], v186, s[82:83] offset:128
	v_or_b32_e32 v187, 16, v72
	v_bitop3_b32 v188, v72, s5, 16 bitop3:0xc8
	v_and_or_b32 v189, v187, 31, v213
	v_cndmask_b32_e32 v108, v189, v188, vcc
	v_lshl_or_b32 v109, v108, 8, v129
	global_load_dwordx4 v[110:113], v109, s[82:83] offset:16
	global_load_dwordx4 v[114:117], v109, s[82:83]
	global_load_dwordx4 v[118:121], v109, s[82:83] offset:144
	global_load_dwordx4 v[122:125], v109, s[82:83] offset:128
	s_nop 0
	s_nop 0
	s_nop 0
	s_nop 0
	s_nop 0
	s_nop 0
	s_nop 0
	s_nop 0
	s_nop 0
	s_nop 0
	s_nop 0
	s_nop 0
	s_waitcnt vmcnt(7)
	v_mul_f32_e32 v82, v26, v93
	s_waitcnt vmcnt(6)
	v_mov_b32_e32 v71, v98
	v_mov_b32_e32 v80, v97
	v_mul_f32_e32 v84, v26, v92
	v_mov_b32_e32 v26, v63
	v_mov_b32_e32 v70, v96
	v_mov_b32_e32 v126, v80
	v_mov_b32_e32 v127, v99
	v_pk_mul_f32 v[74:75], v[60:61], v[126:127]
	v_mov_b32_e32 v148, v80
	v_mov_b32_e32 v149, v99
	v_pk_mul_f32 v[78:79], v[24:25], v[148:149]
	v_mul_f32_e32 v80, v62, v92
	v_mul_f32_e32 v86, v62, v93
	v_pk_mul_f32 v[66:67], v[26:27], v[94:95]
	v_mov_b32_e32 v62, v27
	v_mov_b32_e32 v81, v66
	v_mov_b32_e32 v83, v67
	v_pk_fma_f32 v[60:61], v[60:61], v[70:71], v[78:79] neg_lo:[0,0,1] neg_hi:[0,0,1]
	v_pk_add_f32 v[66:67], v[80:81], v[82:83] neg_lo:[0,1] neg_hi:[0,1]
	v_pk_mul_f32 v[26:27], v[62:63], v[94:95]
	v_pk_fma_f32 v[24:25], v[24:25], v[70:71], v[74:75]
	s_nop 0
	s_nop 0
	v_mov_b32_e32 v85, v26
	v_mov_b32_e32 v87, v27
	v_pk_add_f32 v[26:27], v[84:85], v[86:87]
	v_or_b32_e32 v77, 48, v72
	s_waitcnt vmcnt(5)
;   template <int NT, int MT> DI void run(f32x4 (&acc)[NT][MT], int mb, int nb) const {
;     ...
; #pragma unroll
;         for (int mt = 0; mt < MT; ++mt) {
;           const int pos = tok_pos(mb + mt * 16);
; #pragma unroll
;           for (int nt = 0; nt < 2; ++nt)
; #pragma unroll
;             for (int j = 0; j < 4; ++j) {
;               const float2 cs = rope[pos * 32 + nt * 16 + g4 + j];
;               const float x1 = acc[q4 * 4 + nt][mt][j], x2 = acc[q4 * 4 + nt + 2][mt][j];
;               acc[q4 * 4 + nt][mt][j] = x1 * cs.x - x2 * cs.y;
;               acc[q4 * 4 + nt + 2][mt][j] = x2 * cs.x + x1 * cs.y;
	v_mul_f32_e32 v82, v14, v101
	s_waitcnt vmcnt(4)
	v_mov_b32_e32 v63, v106
	v_mov_b32_e32 v80, v105
	v_mov_b32_e32 v62, v104
	v_mov_b32_e32 v150, v80
	v_mov_b32_e32 v151, v107
	v_pk_mul_f32 v[74:75], v[48:49], v[150:151]
	v_mov_b32_e32 v152, v80
	v_mov_b32_e32 v153, v107
	v_pk_mul_f32 v[78:79], v[12:13], v[152:153]
	v_mul_f32_e32 v80, v50, v100
	v_mul_f32_e32 v84, v14, v100
	v_mul_f32_e32 v86, v50, v101
	v_mov_b32_e32 v14, v51
	v_mov_b32_e32 v50, v15
	v_pk_fma_f32 v[12:13], v[12:13], v[62:63], v[74:75]
	s_nop 0
	v_pk_mul_f32 v[68:69], v[14:15], v[102:103]
	v_pk_mul_f32 v[14:15], v[50:51], v[102:103]
	s_nop 0
	s_nop 0
	s_nop 0
	v_mov_b32_e32 v81, v68
	v_mov_b32_e32 v83, v69
	v_mov_b32_e32 v85, v14
	v_mov_b32_e32 v87, v15
	s_nop 0
	v_pk_fma_f32 v[48:49], v[48:49], v[62:63], v[78:79] neg_lo:[0,0,1] neg_hi:[0,0,1]
	v_pk_add_f32 v[68:69], v[80:81], v[82:83] neg_lo:[0,1] neg_hi:[0,1]
	v_pk_add_f32 v[14:15], v[84:85], v[86:87]
	s_nop 0
	s_nop 0
	s_movk_i32 s5, 0x3fe0
	v_cmp_gt_i32_e32 vcc, s5, v72
	s_movk_i32 s5, 0x1fef
	s_waitcnt vmcnt(3)
	v_mul_f32_e32 v86, v58, v111
	s_waitcnt vmcnt(2)
	v_mov_b32_e32 v51, v116
	v_mov_b32_e32 v84, v115
	v_mov_b32_e32 v50, v114
	v_mov_b32_e32 v154, v84
	v_mov_b32_e32 v155, v117
	v_pk_mul_f32 v[62:63], v[56:57], v[154:155]
	v_mov_b32_e32 v156, v84
	v_mov_b32_e32 v157, v117
	v_pk_mul_f32 v[70:71], v[20:21], v[156:157]
	v_mul_f32_e32 v82, v58, v110
	v_mul_f32_e32 v84, v22, v111
	v_mul_f32_e32 v78, v22, v110
	v_mov_b32_e32 v22, v59
	v_mov_b32_e32 v58, v23
	v_pk_mul_f32 v[88:89], v[22:23], v[112:113]
	v_pk_mul_f32 v[22:23], v[58:59], v[112:113]
	v_mov_b32_e32 v83, v88
	v_mov_b32_e32 v85, v89
	v_mov_b32_e32 v79, v22
	v_mov_b32_e32 v87, v23
	v_pk_fma_f32 v[56:57], v[56:57], v[50:51], v[70:71] neg_lo:[0,0,1] neg_hi:[0,0,1]
	v_pk_add_f32 v[70:71], v[82:83], v[84:85] neg_lo:[0,1] neg_hi:[0,1]
	v_pk_add_f32 v[22:23], v[78:79], v[86:87]
	s_nop 0
	s_nop 0
	v_pk_fma_f32 v[20:21], v[20:21], v[50:51], v[62:63]
	v_or_b32_e32 v75, 32, v72
	s_waitcnt vmcnt(1)
	v_mul_f32_e32 v86, v42, v119
	s_waitcnt vmcnt(0)
	v_mov_b32_e32 v64, v129
	v_mov_b32_e32 v65, v91
	v_mov_b32_e32 v74, v187
	v_mov_b32_e32 v78, v118
	v_mov_b32_e32 v79, v119
	v_mov_b32_e32 v80, v120
	v_mov_b32_e32 v81, v121
	v_mov_b32_e32 v82, v122
	v_mov_b32_e32 v83, v123
	v_mov_b32_e32 v84, v124
	v_mov_b32_e32 v85, v125
	v_bitop3_b32 v90, v72, s5, 32 bitop3:0xc8
	v_cndmask_b32_e32 v91, v65, v90, vcc
	v_lshl_or_b32 v128, v91, 8, v64
	global_load_dwordx4 v[186:189], v128, s[82:83] offset:16
	global_load_dwordx4 v[92:95], v128, s[82:83]
	s_movk_i32 s5, 0x3fd0
	v_cmp_gt_i32_e32 vcc, s5, v72
	s_movk_i32 s5, 0x1fff
	global_load_dwordx4 v[96:99], v128, s[82:83] offset:144
	global_load_dwordx4 v[100:103], v128, s[82:83] offset:128
	v_bitop3_b32 v129, v72, s5, 48 bitop3:0xc8
	v_and_or_b32 v104, v77, 31, v213
	v_cndmask_b32_e32 v105, v104, v129, vcc
	v_lshl_or_b32 v106, v105, 8, v64
	global_load_dwordx4 v[108:111], v106, s[82:83] offset:16
	global_load_dwordx4 v[112:115], v106, s[82:83]
	global_load_dwordx4 v[116:119], v106, s[82:83] offset:144
	global_load_dwordx4 v[120:123], v106, s[82:83] offset:128
	v_mov_b32_e32 v59, v84
	v_mov_b32_e32 v84, v83
	v_mov_b32_e32 v58, v82
	v_pk_mul_f32 v[62:63], v[40:41], v[84:85]
	v_pk_mul_f32 v[50:51], v[4:5], v[84:85]
	v_mul_f32_e32 v82, v42, v78
	v_mul_f32_e32 v84, v6, v79
	v_mul_f32_e32 v78, v6, v78
	v_mov_b32_e32 v6, v43
	v_mov_b32_e32 v42, v7
	v_pk_mul_f32 v[88:89], v[6:7], v[80:81]
	v_pk_mul_f32 v[6:7], v[42:43], v[80:81]
	s_nop 0
	s_nop 0
	v_mov_b32_e32 v83, v88
	v_mov_b32_e32 v85, v89
	v_mov_b32_e32 v79, v6
	v_mov_b32_e32 v87, v7
	s_nop 0
	v_pk_fma_f32 v[40:41], v[40:41], v[58:59], v[50:51] neg_lo:[0,0,1] neg_hi:[0,0,1]
	v_pk_add_f32 v[50:51], v[82:83], v[84:85] neg_lo:[0,1] neg_hi:[0,1]
	v_pk_add_f32 v[6:7], v[78:79], v[86:87]
	s_nop 0
	s_nop 0
	v_pk_fma_f32 v[4:5], v[4:5], v[58:59], v[62:63]
	s_nop 0
	s_nop 0
	s_nop 0
	s_waitcnt vmcnt(7)
	v_mul_f32_e32 v86, v54, v187
	s_waitcnt vmcnt(6)
;   template <int NT, int MT> DI void run(f32x4 (&acc)[NT][MT], int mb, int nb) const {
;     ...
; #pragma unroll
;         for (int mt = 0; mt < MT; ++mt) {
;           const int pos = tok_pos(mb + mt * 16);
; #pragma unroll
;           for (int nt = 0; nt < 2; ++nt)
; #pragma unroll
;             for (int j = 0; j < 4; ++j) {
;               const float2 cs = rope[pos * 32 + nt * 16 + g4 + j];
;               const float x1 = acc[q4 * 4 + nt][mt][j], x2 = acc[q4 * 4 + nt + 2][mt][j];
;               acc[q4 * 4 + nt][mt][j] = x1 * cs.x - x2 * cs.y;
;               acc[q4 * 4 + nt + 2][mt][j] = x2 * cs.x + x1 * cs.y;
	v_mov_b32_e32 v43, v94
	v_mov_b32_e32 v84, v93
	v_mov_b32_e32 v42, v92
	v_mov_b32_e32 v124, v84
	v_mov_b32_e32 v125, v95
	v_pk_mul_f32 v[62:63], v[52:53], v[124:125]
	v_mov_b32_e32 v126, v84
	v_mov_b32_e32 v127, v95
	v_pk_mul_f32 v[58:59], v[16:17], v[126:127]
	v_mul_f32_e32 v82, v54, v186
	v_mul_f32_e32 v84, v18, v187
	v_mul_f32_e32 v78, v18, v186
	v_mov_b32_e32 v18, v55
	v_mov_b32_e32 v54, v19
	v_pk_mul_f32 v[88:89], v[18:19], v[188:189]
	v_pk_mul_f32 v[18:19], v[54:55], v[188:189]
	v_mov_b32_e32 v83, v88
	v_mov_b32_e32 v85, v89
	v_mov_b32_e32 v79, v18
	v_mov_b32_e32 v87, v19
	v_pk_fma_f32 v[52:53], v[52:53], v[42:43], v[58:59] neg_lo:[0,0,1] neg_hi:[0,0,1]
	v_pk_add_f32 v[58:59], v[82:83], v[84:85] neg_lo:[0,1] neg_hi:[0,1]
	v_pk_add_f32 v[18:19], v[78:79], v[86:87]
	s_nop 0
	s_nop 0
	v_pk_fma_f32 v[16:17], v[16:17], v[42:43], v[62:63]
	s_waitcnt vmcnt(5)
	v_mul_f32_e32 v86, v34, v97
	s_waitcnt vmcnt(4)
	v_mov_b32_e32 v55, v102
	v_mov_b32_e32 v84, v101
	v_mov_b32_e32 v54, v100
	v_mov_b32_e32 v148, v84
	v_mov_b32_e32 v149, v103
	v_pk_mul_f32 v[62:63], v[32:33], v[148:149]
	v_mov_b32_e32 v150, v84
	v_mov_b32_e32 v151, v103
	v_pk_mul_f32 v[42:43], v[0:1], v[150:151]
	v_mul_f32_e32 v82, v34, v96
	v_mul_f32_e32 v84, v2, v97
	v_mul_f32_e32 v78, v2, v96
	v_mov_b32_e32 v2, v35
	v_mov_b32_e32 v34, v3
	v_pk_mul_f32 v[88:89], v[2:3], v[98:99]
	v_pk_mul_f32 v[2:3], v[34:35], v[98:99]
	s_nop 0
	s_nop 0
	s_nop 0
	v_mov_b32_e32 v83, v88
	v_mov_b32_e32 v79, v2
	v_mov_b32_e32 v87, v3
	s_nop 0
	v_pk_fma_f32 v[0:1], v[0:1], v[54:55], v[62:63]
	v_pk_add_f32 v[2:3], v[78:79], v[86:87]
	s_nop 0
	s_nop 0
	v_mov_b32_e32 v85, v89
	v_pk_fma_f32 v[32:33], v[32:33], v[54:55], v[42:43] neg_lo:[0,0,1] neg_hi:[0,0,1]
	v_pk_add_f32 v[42:43], v[82:83], v[84:85] neg_lo:[0,1] neg_hi:[0,1]
	s_waitcnt vmcnt(3)
	v_mul_f32_e32 v82, v10, v109
	s_waitcnt vmcnt(2)
	v_mov_b32_e32 v35, v114
	v_mov_b32_e32 v80, v113
	v_mov_b32_e32 v34, v112
	v_mov_b32_e32 v152, v80
	v_mov_b32_e32 v153, v115
	v_pk_mul_f32 v[78:79], v[44:45], v[152:153]
	v_mov_b32_e32 v154, v80
	v_mov_b32_e32 v155, v115
	v_pk_mul_f32 v[54:55], v[8:9], v[154:155]
	v_mul_f32_e32 v80, v46, v108
	v_mul_f32_e32 v62, v10, v108
	v_mul_f32_e32 v84, v46, v109
	v_mov_b32_e32 v10, v47
	v_mov_b32_e32 v46, v11
	v_pk_mul_f32 v[86:87], v[10:11], v[110:111]
	v_pk_mul_f32 v[10:11], v[46:47], v[110:111]
	v_mov_b32_e32 v81, v86
	v_mov_b32_e32 v83, v87
	v_mov_b32_e32 v63, v10
	v_mov_b32_e32 v85, v11
	v_pk_fma_f32 v[44:45], v[44:45], v[34:35], v[54:55] neg_lo:[0,0,1] neg_hi:[0,0,1]
	v_pk_add_f32 v[54:55], v[80:81], v[82:83] neg_lo:[0,1] neg_hi:[0,1]
	v_pk_fma_f32 v[8:9], v[8:9], v[34:35], v[78:79]
	v_pk_add_f32 v[10:11], v[62:63], v[84:85]
	s_nop 0
	s_nop 0
	s_waitcnt vmcnt(1)
	v_mul_f32_e32 v82, v38, v117
	s_waitcnt vmcnt(0)
	v_mov_b32_e32 v35, v122
	v_mov_b32_e32 v80, v121
	v_mov_b32_e32 v34, v120
	v_mov_b32_e32 v156, v80
	v_mov_b32_e32 v157, v123
	v_pk_mul_f32 v[46:47], v[28:29], v[156:157]
	v_mov_b32_e32 v158, v80
	v_mov_b32_e32 v159, v123
	v_pk_mul_f32 v[78:79], v[36:37], v[158:159]
	v_mul_f32_e32 v80, v30, v116
	v_mul_f32_e32 v62, v38, v116
	v_mov_b32_e32 v38, v31
	v_mul_f32_e32 v84, v30, v117
	v_pk_mul_f32 v[86:87], v[38:39], v[118:119]
	v_mov_b32_e32 v30, v39
	v_mov_b32_e32 v81, v86
	v_mov_b32_e32 v83, v87
	v_pk_mul_f32 v[30:31], v[30:31], v[118:119]
	v_pk_fma_f32 v[28:29], v[28:29], v[34:35], v[78:79] neg_lo:[0,0,1] neg_hi:[0,0,1]
	v_pk_add_f32 v[78:79], v[80:81], v[82:83] neg_lo:[0,1] neg_hi:[0,1]
	v_mov_b32_e32 v63, v30
	v_mov_b32_e32 v85, v31
	v_pk_fma_f32 v[36:37], v[36:37], v[34:35], v[46:47]
	v_pk_add_f32 v[38:39], v[62:63], v[84:85]
	v_mov_b32_e32 v30, v78
	v_mov_b32_e32 v31, v79
	v_mov_b32_e32 v34, v42
	v_mov_b32_e32 v35, v43
	v_mov_b32_e32 v42, v50
	v_mov_b32_e32 v43, v51
	v_mov_b32_e32 v50, v68
	v_mov_b32_e32 v51, v69
	v_mov_b32_e32 v46, v54
	v_mov_b32_e32 v47, v55
	v_mov_b32_e32 v54, v58
	v_mov_b32_e32 v55, v59
	v_mov_b32_e32 v58, v70
	v_mov_b32_e32 v59, v71
	v_mov_b32_e32 v62, v66
	v_mov_b32_e32 v63, v67
	v_mov_b32_e32 v64, v118
	v_mov_b32_e32 v65, v119
	v_mov_b32_e32 v88, v106
	s_branch .LBB0_979
